# stack7 + WKVB touch-prefetch at P6 start only
# speedup vs baseline: 1.0088x; 1.0042x over previous
.LBB0_783:
	s_or_b64 exec, exec, s[0:1]
	s_waitcnt vmcnt(7) lgkmcnt(0)
	v_mov_b32_e32 v0, v210
	s_barrier
	v_lshl_add_u32 v236, s2, 9, v210
	v_mov_b32_e32 v237, 0
	v_lshlrev_b64 v[236:237], 7, v[236:237]
	s_add_u32 s98, s92, 0x1400000
	s_addc_u32 s99, s93, 0
	v_lshl_add_u64 v[236:237], s[98:99], 0, v[236:237]
	global_load_dword v234, v[236:237], off
	s_mov_b64 s[100:101], 0x1000000
	v_lshl_add_u64 v[236:237], v[236:237], 0, s[100:101]
	global_load_dword v234, v[236:237], off
	s_cmpk_lt_i32 s2, 0x60
	s_cselect_b64 s[0:1], -1, 0
	v_readfirstlane_b32 s4, v0
	s_cmp_lt_u32 s4, 64
	s_cselect_b64 s[4:5], -1, 0
	s_and_b64 s[0:1], s[4:5], s[0:1]
	s_and_b64 vcc, exec, s[0:1]
	s_cbranch_vccz .LBB0_786
	v_mbcnt_hi_u32_b32 v1, -1, v211
	s_waitcnt vmcnt(6)
	v_and_b32_e32 v7, 64, v1
	v_add_u32_e32 v2, -1, v1
	v_cmp_lt_i32_e32 vcc, v2, v7
	v_add_u32_e32 v3, -2, v1
	v_add_u32_e32 v4, -4, v1
	v_cndmask_b32_e32 v2, v2, v1, vcc
	v_cmp_lt_i32_e32 vcc, v3, v7
	v_add_u32_e32 v5, -8, v1
	v_add_u32_e32 v6, -16, v1
	v_cndmask_b32_e32 v3, v3, v1, vcc
	v_cmp_lt_i32_e32 vcc, v4, v7
	s_waitcnt vmcnt(5)
	v_subrev_u32_e32 v8, 32, v1
	s_lshl_b64 s[0:1], s[2:3], 13
	v_cndmask_b32_e32 v4, v4, v1, vcc
	v_cmp_lt_i32_e32 vcc, v5, v7
	v_and_b32_e32 v0, 63, v0
	s_add_u32 s0, s92, s0
	v_cndmask_b32_e32 v5, v5, v1, vcc
	v_cmp_lt_i32_e32 vcc, v6, v7
	v_cmp_gt_u32_e64 s[42:43], 32, v0
	v_cmp_gt_u32_e64 s[44:45], 16, v0
	v_cndmask_b32_e32 v6, v6, v1, vcc
	v_cmp_lt_i32_e32 vcc, v8, v7
	v_cmp_gt_u32_e64 s[46:47], 8, v0
	v_cmp_gt_u32_e64 s[48:49], 4, v0
	v_cndmask_b32_e32 v1, v8, v1, vcc
	v_cmp_gt_u32_e64 s[50:51], 2, v0
	v_cmp_eq_u32_e64 s[52:53], 0, v0
	v_lshlrev_b32_e32 v7, 2, v1
	v_lshlrev_b32_e32 v0, 7, v0
	v_mov_b32_e32 v1, 0
	s_addc_u32 s1, s93, s1
	v_lshl_add_u64 v[0:1], s[0:1], 0, v[0:1]
	s_mov_b64 s[0:1], 0x120000
	v_lshlrev_b32_e32 v2, 2, v2
	v_lshlrev_b32_e32 v3, 2, v3
	v_lshlrev_b32_e32 v4, 2, v4
	v_lshlrev_b32_e32 v5, 2, v5
	v_lshlrev_b32_e32 v6, 2, v6
	v_lshl_add_u64 v[0:1], v[0:1], 0, s[0:1]
	s_lshl_b64 s[0:1], s[94:95], 13
	s_mov_b32 s4, s2
	s_mov_b32 s5, 0xfff31000
